# prompt pool units: Wpool fragment loads with contiguous lane order + ds_bpermute to the MFMA layout
# speedup vs baseline: 1.0032x; 1.0032x over previous
.LBB0_555:
	v_and_b32_e32 v212, 63, v204
	v_lshrrev_b32_e32 v213, 4, v212
	v_and_b32_e32 v212, 15, v212
	v_lshlrev_b32_e32 v213, 2, v213
	v_lshl_or_b32 v212, v212, 4, v213
	ds_bpermute_b32 v2, v212, v2
	ds_bpermute_b32 v3, v212, v3
	ds_bpermute_b32 v4, v212, v4
	ds_bpermute_b32 v5, v212, v5
	ds_bpermute_b32 v6, v212, v6
	ds_bpermute_b32 v7, v212, v7
	ds_bpermute_b32 v8, v212, v8
	ds_bpermute_b32 v9, v212, v9
	ds_bpermute_b32 v10, v212, v10
	ds_bpermute_b32 v11, v212, v11
	ds_bpermute_b32 v12, v212, v12
	ds_bpermute_b32 v13, v212, v13
	ds_bpermute_b32 v14, v212, v14
	ds_bpermute_b32 v15, v212, v15
	ds_bpermute_b32 v16, v212, v16
	ds_bpermute_b32 v17, v212, v17
	s_waitcnt lgkmcnt(0)
	ds_bpermute_b32 v18, v212, v18
	ds_bpermute_b32 v19, v212, v19
	ds_bpermute_b32 v20, v212, v20
	ds_bpermute_b32 v21, v212, v21
	ds_bpermute_b32 v22, v212, v22
	ds_bpermute_b32 v23, v212, v23
	ds_bpermute_b32 v24, v212, v24
	ds_bpermute_b32 v25, v212, v25
	ds_bpermute_b32 v26, v212, v26
	ds_bpermute_b32 v27, v212, v27
	ds_bpermute_b32 v28, v212, v28
	ds_bpermute_b32 v29, v212, v29
	ds_bpermute_b32 v30, v212, v30
	ds_bpermute_b32 v31, v212, v31
	ds_bpermute_b32 v32, v212, v32
	ds_bpermute_b32 v33, v212, v33
	s_waitcnt lgkmcnt(0)
	ds_bpermute_b32 v34, v212, v34
	ds_bpermute_b32 v35, v212, v35
	ds_bpermute_b32 v36, v212, v36
	ds_bpermute_b32 v37, v212, v37
	ds_bpermute_b32 v38, v212, v38
	ds_bpermute_b32 v39, v212, v39
	ds_bpermute_b32 v40, v212, v40
	ds_bpermute_b32 v41, v212, v41
	ds_bpermute_b32 v42, v212, v42
	ds_bpermute_b32 v43, v212, v43
	ds_bpermute_b32 v44, v212, v44
	ds_bpermute_b32 v45, v212, v45
	ds_bpermute_b32 v46, v212, v46
	ds_bpermute_b32 v47, v212, v47
	ds_bpermute_b32 v48, v212, v48
	ds_bpermute_b32 v49, v212, v49
	s_waitcnt lgkmcnt(0)
	ds_bpermute_b32 v50, v212, v50
	ds_bpermute_b32 v51, v212, v51
	ds_bpermute_b32 v52, v212, v52
	ds_bpermute_b32 v53, v212, v53
	ds_bpermute_b32 v54, v212, v54
	ds_bpermute_b32 v55, v212, v55
	ds_bpermute_b32 v56, v212, v56
	ds_bpermute_b32 v57, v212, v57
	ds_bpermute_b32 v58, v212, v58
	ds_bpermute_b32 v59, v212, v59
	ds_bpermute_b32 v60, v212, v60
	ds_bpermute_b32 v61, v212, v61
	ds_bpermute_b32 v62, v212, v62
	ds_bpermute_b32 v63, v212, v63
	ds_bpermute_b32 v64, v212, v64
	ds_bpermute_b32 v65, v212, v65
	s_waitcnt lgkmcnt(0)
	ds_bpermute_b32 v66, v212, v66
	ds_bpermute_b32 v67, v212, v67
	ds_bpermute_b32 v68, v212, v68
	ds_bpermute_b32 v69, v212, v69
	ds_bpermute_b32 v70, v212, v70
	ds_bpermute_b32 v71, v212, v71
	ds_bpermute_b32 v72, v212, v72
	ds_bpermute_b32 v73, v212, v73
	ds_bpermute_b32 v74, v212, v74
	ds_bpermute_b32 v75, v212, v75
	ds_bpermute_b32 v76, v212, v76
	ds_bpermute_b32 v77, v212, v77
	ds_bpermute_b32 v78, v212, v78
	ds_bpermute_b32 v79, v212, v79
	ds_bpermute_b32 v80, v212, v80
	ds_bpermute_b32 v81, v212, v81
	s_waitcnt lgkmcnt(0)
	ds_bpermute_b32 v82, v212, v82
	ds_bpermute_b32 v83, v212, v83
	ds_bpermute_b32 v84, v212, v84
	ds_bpermute_b32 v85, v212, v85
	ds_bpermute_b32 v86, v212, v86
	ds_bpermute_b32 v87, v212, v87
	ds_bpermute_b32 v88, v212, v88
	ds_bpermute_b32 v89, v212, v89
	ds_bpermute_b32 v90, v212, v90
	ds_bpermute_b32 v91, v212, v91
	ds_bpermute_b32 v92, v212, v92
	ds_bpermute_b32 v93, v212, v93
	ds_bpermute_b32 v94, v212, v94
	ds_bpermute_b32 v95, v212, v95
	ds_bpermute_b32 v96, v212, v96
	ds_bpermute_b32 v97, v212, v97
	s_waitcnt lgkmcnt(0)
	ds_bpermute_b32 v98, v212, v98
	ds_bpermute_b32 v99, v212, v99
	ds_bpermute_b32 v100, v212, v100
	ds_bpermute_b32 v101, v212, v101
	ds_bpermute_b32 v102, v212, v102
	ds_bpermute_b32 v103, v212, v103
	ds_bpermute_b32 v104, v212, v104
	ds_bpermute_b32 v105, v212, v105
	ds_bpermute_b32 v106, v212, v106
	ds_bpermute_b32 v107, v212, v107
	ds_bpermute_b32 v108, v212, v108
	ds_bpermute_b32 v109, v212, v109
	ds_bpermute_b32 v110, v212, v110
	ds_bpermute_b32 v111, v212, v111
	ds_bpermute_b32 v112, v212, v112
	ds_bpermute_b32 v113, v212, v113
	s_waitcnt lgkmcnt(0)
	ds_bpermute_b32 v114, v212, v114
	ds_bpermute_b32 v115, v212, v115
	ds_bpermute_b32 v116, v212, v116
	ds_bpermute_b32 v117, v212, v117
	ds_bpermute_b32 v118, v212, v118
	ds_bpermute_b32 v119, v212, v119
	ds_bpermute_b32 v120, v212, v120
	ds_bpermute_b32 v121, v212, v121
	ds_bpermute_b32 v122, v212, v122
	ds_bpermute_b32 v123, v212, v123
	ds_bpermute_b32 v124, v212, v124
	ds_bpermute_b32 v125, v212, v125
	ds_bpermute_b32 v126, v212, v126
	ds_bpermute_b32 v127, v212, v127
	ds_bpermute_b32 v128, v212, v128
	ds_bpermute_b32 v129, v212, v129
	s_waitcnt lgkmcnt(0)
	s_add_i32 s0, s19, s22
	v_add3_u32 v0, s0, 1, v176
	v_min_i32_e32 v0, s24, v0
	v_cvt_f32_i32_e32 v0, v0
	s_lshl_b32 s72, s23, 1
	v_div_scale_f32 v212, s[0:1], v0, v0, 1.0
	v_rcp_f32_e32 v213, v212
	v_div_scale_f32 v214, vcc, 1.0, v0, 1.0
	v_fma_f32 v215, -v212, v213, 1.0
	v_fmac_f32_e32 v213, v215, v213
	v_mul_f32_e32 v215, v214, v213
	v_fma_f32 v222, -v212, v215, v214
	v_fmac_f32_e32 v215, v222, v213
	v_fma_f32 v212, -v212, v215, v214
	v_div_fmas_f32 v212, v212, v213, v215
	v_div_fixup_f32 v0, v212, v0, 1.0
	v_pk_fma_f32 v[138:139], v[0:1], v[144:145], v[138:139] op_sel_hi:[0,1,1] neg_lo:[0,0,1] neg_hi:[0,0,1]
	v_pk_fma_f32 v[136:137], v[0:1], v[142:143], v[136:137] op_sel_hi:[0,1,1] neg_lo:[0,0,1] neg_hi:[0,0,1]
	v_pk_fma_f32 v[134:135], v[0:1], v[140:141], v[134:135] op_sel_hi:[0,1,1] neg_lo:[0,0,1] neg_hi:[0,0,1]
	v_pk_fma_f32 v[130:131], v[0:1], v[132:133], v[130:131] op_sel_hi:[0,1,1] neg_lo:[0,0,1] neg_hi:[0,0,1]
	v_cvt_pk_bf16_f32 v138, v138, v139
	v_cvt_pk_bf16_f32 v139, v136, v137
	v_cvt_pk_bf16_f32 v140, v134, v135
	v_cvt_pk_bf16_f32 v141, v130, v131
	v_pk_fma_f32 v[154:155], v[0:1], v[160:161], v[154:155] op_sel_hi:[0,1,1] neg_lo:[0,0,1] neg_hi:[0,0,1]
	v_pk_fma_f32 v[152:153], v[0:1], v[158:159], v[152:153] op_sel_hi:[0,1,1] neg_lo:[0,0,1] neg_hi:[0,0,1]
	v_mfma_f32_16x16x32_bf16 v[94:97], v[94:97], v[138:141], 0
	v_fma_f32 v150, v0, v156, -v150
	v_fma_f32 v151, v0, v157, -v151
	v_pk_fma_f32 v[146:147], v[0:1], v[146:147], v[148:149] op_sel_hi:[0,1,1] neg_lo:[0,0,1] neg_hi:[0,0,1]
	v_cvt_pk_bf16_f32 v154, v154, v155
	v_mfma_f32_16x16x32_bf16 v[38:41], v[38:41], v[138:141], 0
	v_cvt_pk_bf16_f32 v155, v152, v153
	v_cvt_pk_bf16_f32 v156, v150, v151
	v_cvt_pk_bf16_f32 v157, v146, v147
	v_pk_fma_f32 v[170:171], v[0:1], v[186:187], v[170:171] op_sel_hi:[0,1,1] neg_lo:[0,0,1] neg_hi:[0,0,1]
	v_pk_fma_f32 v[174:175], v[0:1], v[174:175], v[168:169] op_sel_hi:[0,1,1] neg_lo:[0,0,1] neg_hi:[0,0,1]
	v_mfma_f32_16x16x32_bf16 v[78:81], v[78:81], v[154:157], v[94:97]
	v_fma_f32 v166, v0, v172, -v166
	v_fma_f32 v167, v0, v173, -v167
	v_pk_fma_f32 v[162:163], v[0:1], v[162:163], v[164:165] op_sel_hi:[0,1,1] neg_lo:[0,0,1] neg_hi:[0,0,1]
	v_cvt_pk_bf16_f32 v168, v170, v171
	v_mfma_f32_16x16x32_bf16 v[38:41], v[42:45], v[154:157], v[38:41]
	v_cvt_pk_bf16_f32 v169, v174, v175
	v_cvt_pk_bf16_f32 v170, v166, v167
	v_cvt_pk_bf16_f32 v171, v162, v163
	v_pk_fma_f32 v[130:131], v[0:1], v[202:203], v[188:189] op_sel_hi:[0,1,1] neg_lo:[0,0,1] neg_hi:[0,0,1]
	v_pk_fma_f32 v[94:95], v[0:1], v[200:201], v[192:193] op_sel_hi:[0,1,1] neg_lo:[0,0,1] neg_hi:[0,0,1]
	v_mfma_f32_16x16x32_bf16 v[66:69], v[66:69], v[168:171], v[78:81]
	v_cvt_pk_bf16_f32 v130, v130, v131
	v_cvt_pk_bf16_f32 v131, v94, v95
	v_pk_fma_f32 v[94:95], v[0:1], v[198:199], v[194:195] op_sel_hi:[0,1,1] neg_lo:[0,0,1] neg_hi:[0,0,1]
	v_mfma_f32_16x16x32_bf16 v[38:41], v[46:49], v[168:171], v[38:41]
	v_fma_f32 v78, v0, v190, -v196
	v_fma_f32 v79, v0, v191, -v197
	v_cvt_pk_bf16_f32 v132, v94, v95
	v_cvt_pk_bf16_f32 v133, v78, v79
	v_mfma_f32_16x16x32_bf16 v[42:45], v[102:105], v[138:141], 0
	v_or_b32_e32 v0, s21, v176
	v_mfma_f32_16x16x32_bf16 v[34:37], v[34:37], v[130:133], v[66:69]
	v_mfma_f32_16x16x32_bf16 v[66:69], v[126:129], v[138:141], 0
	v_mfma_f32_16x16x32_bf16 v[38:41], v[50:53], v[130:133], v[38:41]
	s_nop 5
	v_cvt_pk_bf16_f32 v34, v34, v35
	v_cvt_pk_bf16_f32 v35, v36, v37
	v_mfma_f32_16x16x32_bf16 v[46:49], v[54:57], v[138:141], 0
	v_add_u32_e32 v54, s19, v0
	v_ashrrev_i32_e32 v55, 31, v54
	v_lshlrev_b64 v[54:55], 11, v[54:55]
	v_mfma_f32_16x16x32_bf16 v[50:53], v[106:109], v[138:141], 0
	v_lshl_add_u64 v[54:55], s[76:77], 0, v[54:55]
	v_lshl_add_u64 v[54:55], v[54:55], 0, s[72:73]
	v_lshlrev_b32_e32 v0, 3, v225
	v_mfma_f32_16x16x32_bf16 v[30:33], v[30:33], v[138:141], 0
	v_lshl_add_u64 v[54:55], v[54:55], 0, v[0:1]
	global_store_dwordx2 v[54:55], v[34:35], off
	v_mfma_f32_16x16x32_bf16 v[14:17], v[14:17], v[138:141], 0
	v_mfma_f32_16x16x32_bf16 v[42:45], v[82:85], v[154:157], v[42:45]
	v_mfma_f32_16x16x32_bf16 v[66:69], v[70:73], v[154:157], v[66:69]
	v_mfma_f32_16x16x32_bf16 v[46:49], v[58:61], v[154:157], v[46:49]
	v_mfma_f32_16x16x32_bf16 v[50:53], v[110:113], v[154:157], v[50:53]
	v_mfma_f32_16x16x32_bf16 v[26:29], v[26:29], v[154:157], v[30:33]
	v_mfma_f32_16x16x32_bf16 v[10:13], v[10:13], v[154:157], v[14:17]
	v_mfma_f32_16x16x32_bf16 v[42:45], v[86:89], v[168:171], v[42:45]
	v_mfma_f32_16x16x32_bf16 v[66:69], v[74:77], v[168:171], v[66:69]
	v_mfma_f32_16x16x32_bf16 v[46:49], v[62:65], v[168:171], v[46:49]
	v_mfma_f32_16x16x32_bf16 v[50:53], v[98:101], v[168:171], v[50:53]
	v_mfma_f32_16x16x32_bf16 v[22:25], v[22:25], v[168:171], v[26:29]
	v_mfma_f32_16x16x32_bf16 v[6:9], v[6:9], v[168:171], v[10:13]
	s_nop 1
	v_cvt_pk_bf16_f32 v26, v38, v39
	v_cvt_pk_bf16_f32 v27, v40, v41
	global_store_dwordx2 v[54:55], v[26:27], off offset:64
	v_mfma_f32_16x16x32_bf16 v[42:45], v[90:93], v[130:133], v[42:45]
	v_mfma_f32_16x16x32_bf16 v[66:69], v[122:125], v[130:133], v[66:69]
	v_mfma_f32_16x16x32_bf16 v[46:49], v[114:117], v[130:133], v[46:49]
	v_mfma_f32_16x16x32_bf16 v[50:53], v[118:121], v[130:133], v[50:53]
	s_nop 5
	v_cvt_pk_bf16_f32 v30, v66, v67
	v_cvt_pk_bf16_f32 v31, v68, v69
	global_store_dwordx2 v[54:55], v[30:31], off offset:32
	v_mfma_f32_16x16x32_bf16 v[18:21], v[18:21], v[130:133], v[22:25]
	v_mfma_f32_16x16x32_bf16 v[2:5], v[2:5], v[130:133], v[6:9]
	s_nop 1
	v_cvt_pk_bf16_f32 v22, v42, v43
	v_cvt_pk_bf16_f32 v23, v44, v45
	global_store_dwordx2 v[54:55], v[22:23], off offset:96
	v_cvt_pk_bf16_f32 v22, v46, v47
	v_cvt_pk_bf16_f32 v23, v48, v49
	v_cvt_pk_bf16_f32 v14, v50, v51
	v_cvt_pk_bf16_f32 v15, v52, v53
	v_cvt_pk_bf16_f32 v10, v18, v19
	v_cvt_pk_bf16_f32 v11, v20, v21
	v_cvt_pk_bf16_f32 v2, v2, v3
	v_cvt_pk_bf16_f32 v3, v4, v5
	global_store_dwordx2 v[54:55], v[22:23], off offset:128
	global_store_dwordx2 v[54:55], v[14:15], off offset:160
	global_store_dwordx2 v[54:55], v[10:11], off offset:192
	global_store_dwordx2 v[54:55], v[2:3], off offset:224

.LBB0_634:
	s_or_b64 exec, exec, s[48:49]
	s_mov_b32 s37, s73
	s_lshl_b64 s[24:25], s[36:37], 15
	s_add_u32 s24, s51, s24
	v_readlane_b32 s12, v253, 20
	v_bfe_u32 v225, v151, 4, 2
	s_addc_u32 s25, s12, s25
	v_lshlrev_b32_e32 v0, 8, v176
	v_lshl_add_u64 v[2:3], s[24:25], 0, v[0:1]
	v_lshlrev_b32_e32 v0, 4, v225
	v_lshl_add_u64 v[2:3], v[2:3], 0, v[0:1]
	v_and_b32_e32 v10, 63, v204
	v_lshrrev_b32_e32 v11, 2, v10
	v_and_b32_e32 v12, 15, v10
	v_sub_u32_e32 v11, v11, v12
	v_lshlrev_b32_e32 v11, 8, v11
	v_and_b32_e32 v12, 3, v10
	v_lshrrev_b32_e32 v13, 4, v10
	v_sub_u32_e32 v12, v12, v13
	v_lshl_add_u32 v10, v12, 4, v11
	v_ashrrev_i32_e32 v11, 31, v10
	v_lshl_add_u64 v[2:3], v[2:3], 0, v[10:11]
	s_movk_i32 s12, 0x1000
	v_add_co_u32_e32 v4, vcc, s12, v2
	s_movk_i32 s12, 0x2000
	s_nop 0
	v_addc_co_u32_e32 v5, vcc, 0, v3, vcc
	v_add_co_u32_e32 v126, vcc, s12, v2
	s_movk_i32 s12, 0x3000
	s_nop 0
	v_addc_co_u32_e32 v127, vcc, 0, v3, vcc
	v_add_co_u32_e32 v6, vcc, s12, v2
	s_movk_i32 s12, 0x4000
	s_nop 0
	v_addc_co_u32_e32 v7, vcc, 0, v3, vcc
	v_add_co_u32_e32 v8, vcc, s12, v2
	s_movk_i32 s12, 0x5000
	s_nop 0
	v_addc_co_u32_e32 v9, vcc, 0, v3, vcc
	global_load_dwordx4 v[94:97], v[2:3], off
	global_load_dwordx4 v[78:81], v[2:3], off offset:64
	global_load_dwordx4 v[66:69], v[2:3], off offset:128
	global_load_dwordx4 v[34:37], v[2:3], off offset:192
	global_load_dwordx4 v[70:73], v[4:5], off offset:64
	global_load_dwordx4 v[74:77], v[4:5], off offset:128
	global_load_dwordx4 v[38:41], v[126:127], off
	global_load_dwordx4 v[42:45], v[126:127], off offset:64
	global_load_dwordx4 v[46:49], v[126:127], off offset:128
	global_load_dwordx4 v[50:53], v[126:127], off offset:192
	global_load_dwordx4 v[122:125], v[4:5], off offset:192
	global_load_dwordx4 v[82:85], v[6:7], off offset:64
	global_load_dwordx4 v[86:89], v[6:7], off offset:128
	global_load_dwordx4 v[90:93], v[6:7], off offset:192
	global_load_dwordx4 v[102:105], v[8:9], off offset:-4096
	global_load_dwordx4 v[54:57], v[8:9], off
	global_load_dwordx4 v[58:61], v[8:9], off offset:64
	global_load_dwordx4 v[62:65], v[8:9], off offset:128
	v_add_co_u32_e32 v4, vcc, s12, v2
	s_movk_i32 s12, 0x6000
	s_nop 0
	v_addc_co_u32_e32 v5, vcc, 0, v3, vcc
	v_add_co_u32_e32 v6, vcc, s12, v2
	v_lshlrev_b32_e32 v150, 4, v151
	s_nop 0
	v_addc_co_u32_e32 v7, vcc, 0, v3, vcc
	global_load_dwordx4 v[114:117], v[8:9], off offset:192
	global_load_dwordx4 v[106:109], v[6:7], off offset:-4096
	global_load_dwordx4 v[110:113], v[4:5], off offset:64
	global_load_dwordx4 v[98:101], v[4:5], off offset:128
	global_load_dwordx4 v[30:33], v[6:7], off
	global_load_dwordx4 v[26:29], v[6:7], off offset:64
	global_load_dwordx4 v[22:25], v[6:7], off offset:128
	global_load_dwordx4 v[18:21], v[6:7], off offset:192
	v_add_co_u32_e32 v2, vcc, 0x7000, v2
	v_and_b32_e32 v150, 0xf0, v150
	s_nop 0
	v_addc_co_u32_e32 v3, vcc, 0, v3, vcc
	global_load_dwordx4 v[118:121], v[4:5], off offset:192
	global_load_dwordx4 v[14:17], v[2:3], off
	global_load_dwordx4 v[10:13], v[2:3], off offset:64
	global_load_dwordx4 v[6:9], v[2:3], off offset:128
	s_nop 0
	global_load_dwordx4 v[126:129], v[126:127], off offset:-4096
	s_nop 0
	global_load_dwordx4 v[2:5], v[2:3], off offset:192
	v_add_u32_e32 v150, 0, v150
	s_and_saveexec_b64 s[48:49], s[0:1]
	s_cbranch_execz .LBB0_644
	s_movk_i32 s0, 0x120
	v_mad_u64_u32 v[158:159], s[0:1], v152, s0, v[150:151]
	s_waitcnt vmcnt(0)
	ds_write_b128 v158, v[134:137]
	s_or_b64 exec, exec, s[48:49]
	s_and_saveexec_b64 s[0:1], s[38:39]
	s_cbranch_execnz .LBB0_645
